# v024 + hand-written per-wave copy engine with arrival polling for the 16 idle workgroups of P7 (moves more of the copy into the HBM-idle phase)
# baseline (speedup 1.0000x reference)
.LBB0_1957:
	s_nop 0
	v_readlane_b32 s8, v242, 2
	v_readlane_b32 s10, v242, 4
	v_readlane_b32 s11, v242, 5
	s_add_u32 s2, s10, 0x1cd00000
	s_addc_u32 s3, s11, 0
	s_cmp_lt_i32 s72, 8
	s_cselect_b64 s[0:1], -1, 0
	s_cmp_gt_i32 s73, 7
	s_cselect_b64 s[4:5], -1, 0
	s_and_b64 s[0:1], s[0:1], s[4:5]
	v_readlane_b32 s9, v242, 3
	s_andn2_b64 vcc, exec, s[0:1]
	s_cbranch_vccnz .LBB0_2096
	s_and_b64 s[0:1], s[58:59], exec
	s_cselect_b32 s33, 0xf0, s84
	s_add_u32 s0, s10, 0x5400
	s_addc_u32 s1, s11, 0
	v_writelane_b32 v242, s0, 30
	v_mov_b32_e32 v149, 0
	v_lshl_add_u64 v[130:131], s[8:9], 0, v[148:149]
	v_writelane_b32 v242, s1, 31
	s_add_u32 s0, s10, 0x5500
	s_addc_u32 s1, s11, 0
	v_writelane_b32 v241, s0, 2
	s_mov_b64 s[4:5], -1
	s_nop 0
	v_writelane_b32 v241, s1, 3
	s_add_u32 s0, s10, 0x5600
	s_addc_u32 s1, s11, 0
	v_writelane_b32 v241, s0, 4
	s_nop 1
	v_writelane_b32 v241, s1, 5
	s_add_u32 s0, s10, 0x5700
	s_addc_u32 s1, s11, 0
	s_add_u32 s14, s10, 0x5800
	s_addc_u32 s15, s11, 0
	s_add_u32 s16, s10, 0x5900
	s_addc_u32 s17, s11, 0
	s_add_u32 s18, s10, 0x5a00
	s_addc_u32 s19, s11, 0
	s_add_u32 s20, s10, 0x5b00
	s_addc_u32 s21, s11, 0
	s_add_u32 s22, s10, 0x5c00
	s_addc_u32 s23, s11, 0
	s_add_u32 s24, s10, 0x5d00
	s_addc_u32 s25, s11, 0
	s_add_u32 s26, s10, 0x5e00
	s_addc_u32 s27, s11, 0
	s_add_u32 s28, s10, 0x5f00
	s_addc_u32 s29, s11, 0
	s_add_u32 s30, s10, 0x6000
	s_addc_u32 s31, s11, 0
	s_add_u32 s34, s10, 0x6100
	s_addc_u32 s35, s11, 0
	s_add_u32 s36, s10, 0x6200
	s_addc_u32 s37, s11, 0
	s_add_u32 s38, s10, 0x6300
	s_addc_u32 s39, s11, 0
	s_ashr_i32 s96, s33, 31
	v_writelane_b32 v241, s0, 6
	s_cmp_gt_u32 s73, 8
	s_nop 0
	v_writelane_b32 v241, s1, 7
	s_cselect_b64 s[0:1], -1, 0
	v_writelane_b32 v241, s0, 8
	s_cmp_lt_i32 s92, s33
	s_nop 0
	v_writelane_b32 v241, s1, 9
	s_cbranch_scc1 .LBB0_1992
	v_mbcnt_lo_u32_b32 v1, -1, 0
	v_mbcnt_hi_u32_b32 v1, -1, v1
	v_lshlrev_b32_e32 v104, 4, v1
	v_add_u32_e32 v105, 0x1000, v104
	v_readlane_b32 s56, v242, 43
	v_readlane_b32 s57, v242, 44
	v_readlane_b32 s60, v242, 2
	v_readlane_b32 s61, v242, 3
	v_readlane_b32 s66, v242, 4
	v_readlane_b32 s67, v242, 5
	v_readlane_b32 s68, v242, 25
	v_mov_b32_e32 v2, 0
	v_mov_b32_e32 v3, 8
	s_mov_b32 s64, 0x10478000
	s_mov_b32 s65, 0x30478000
	s_add_u32 s66, s66, 0x5400
	s_addc_u32 s67, s67, 0
	s_mul_i32 s68, s68, s84
	s_mov_b64 s[62:63], exec
.Lcpw_loop_P7:
	s_mov_b64 exec, 1
	global_load_dword v8, v2, s[66:67] sc1
	global_load_dword v9, v2, s[66:67] offset:256 sc1
	global_load_dword v10, v2, s[66:67] offset:512 sc1
	global_load_dword v11, v2, s[66:67] offset:768 sc1
	global_load_dword v12, v2, s[66:67] offset:1024 sc1
	global_load_dword v13, v2, s[66:67] offset:1280 sc1
	global_load_dword v14, v2, s[66:67] offset:1536 sc1
	global_load_dword v15, v2, s[66:67] offset:1792 sc1
	global_load_dword v16, v2, s[66:67] offset:2048 sc1
	global_load_dword v17, v2, s[66:67] offset:2304 sc1
	global_load_dword v18, v2, s[66:67] offset:2560 sc1
	global_load_dword v19, v2, s[66:67] offset:2816 sc1
	global_load_dword v20, v2, s[66:67] offset:3072 sc1
	global_load_dword v21, v2, s[66:67] offset:3328 sc1
	global_load_dword v22, v2, s[66:67] offset:3584 sc1
	global_load_dword v23, v2, s[66:67] offset:3840 sc1
	s_waitcnt vmcnt(0)
	v_add_u32_e32 v8, v8, v9
	v_add_u32_e32 v8, v8, v10
	v_add_u32_e32 v8, v8, v11
	v_add_u32_e32 v8, v8, v12
	v_add_u32_e32 v8, v8, v13
	v_add_u32_e32 v8, v8, v14
	v_add_u32_e32 v8, v8, v15
	v_add_u32_e32 v8, v8, v16
	v_add_u32_e32 v8, v8, v17
	v_add_u32_e32 v8, v8, v18
	v_add_u32_e32 v8, v8, v19
	v_add_u32_e32 v8, v8, v20
	v_add_u32_e32 v8, v8, v21
	v_add_u32_e32 v8, v8, v22
	v_add_u32_e32 v8, v8, v23
	s_nop 1
	v_readfirstlane_b32 s69, v8
	s_nop 3
	s_sub_u32 s69, s69, s68
	s_cmp_ge_u32 s69, 16
	s_cbranch_scc1 .Lcpw_exit_P7
	global_atomic_add v4, v2, v3, s[56:57] sc0
	s_waitcnt vmcnt(0)
	v_readfirstlane_b32 s4, v4
	s_nop 3
	s_mov_b64 exec, s[62:63]
	s_cmp_ge_u32 s4, 0x1fe00
	s_cbranch_scc1 .Lcpw_exit_P7
	s_mov_b32 s5, 0
.Lcpw_trip_P7:
	s_add_i32 s6, s4, s5
	s_add_i32 s7, s6, 1
	s_cmp_ge_u32 s6, 0xff00
	s_cselect_b32 s8, s46, s44
	s_cselect_b32 s9, s47, s45
	s_cselect_b32 s55, s65, s64
	s_cselect_b32 s52, 0xff00, 0
	s_sub_u32 s52, s6, s52
	s_mul_hi_i32 s53, s52, 0x80808081
	s_add_i32 s53, s53, s52
	s_lshr_b32 s54, s53, 31
	s_ashr_i32 s53, s53, 8
	s_add_i32 s53, s53, s54
	s_mul_i32 s54, s53, 0x1fe
	s_sub_u32 s54, s52, s54
	s_lshl_b32 s53, s53, 22
	s_lshl_b32 s54, s54, 13
	s_add_u32 s53, s53, s54
	s_add_u32 s55, s55, s53
	s_add_u32 s53, s53, 0x4000
	s_add_u32 s8, s8, s53
	s_addc_u32 s9, s9, 0
	s_add_u32 s10, s60, s55
	s_addc_u32 s11, s61, 0
	s_cmp_ge_u32 s7, 0xff00
	s_cselect_b32 s12, s46, s44
	s_cselect_b32 s13, s47, s45
	s_cselect_b32 s55, s65, s64
	s_cselect_b32 s52, 0xff00, 0
	s_sub_u32 s52, s7, s52
	s_mul_hi_i32 s53, s52, 0x80808081
	s_add_i32 s53, s53, s52
	s_lshr_b32 s54, s53, 31
	s_ashr_i32 s53, s53, 8
	s_add_i32 s53, s53, s54
	s_mul_i32 s54, s53, 0x1fe
	s_sub_u32 s54, s52, s54
	s_lshl_b32 s53, s53, 22
	s_lshl_b32 s54, s54, 13
	s_add_u32 s53, s53, s54
	s_add_u32 s55, s55, s53
	s_add_u32 s53, s53, 0x4000
	s_add_u32 s12, s12, s53
	s_addc_u32 s13, s13, 0
	s_add_u32 s50, s60, s55
	s_addc_u32 s51, s61, 0
	global_load_dwordx4 v[40:43], v104, s[8:9] nt
	global_load_dwordx4 v[44:47], v104, s[8:9] offset:1024 nt
	global_load_dwordx4 v[48:51], v104, s[8:9] offset:2048 nt
	global_load_dwordx4 v[52:55], v104, s[8:9] offset:3072 nt
	global_load_dwordx4 v[56:59], v105, s[8:9] nt
	global_load_dwordx4 v[60:63], v105, s[8:9] offset:1024 nt
	global_load_dwordx4 v[64:67], v105, s[8:9] offset:2048 nt
	global_load_dwordx4 v[68:71], v105, s[8:9] offset:3072 nt
	global_load_dwordx4 v[72:75], v104, s[12:13] nt
	global_load_dwordx4 v[76:79], v104, s[12:13] offset:1024 nt
	global_load_dwordx4 v[80:83], v104, s[12:13] offset:2048 nt
	global_load_dwordx4 v[84:87], v104, s[12:13] offset:3072 nt
	global_load_dwordx4 v[88:91], v105, s[12:13] nt
	global_load_dwordx4 v[92:95], v105, s[12:13] offset:1024 nt
	global_load_dwordx4 v[96:99], v105, s[12:13] offset:2048 nt
	global_load_dwordx4 v[100:103], v105, s[12:13] offset:3072 nt
	s_waitcnt vmcnt(0)
	global_store_dwordx4 v104, v[40:43], s[10:11] nt
	global_store_dwordx4 v104, v[44:47], s[10:11] offset:1024 nt
	global_store_dwordx4 v104, v[48:51], s[10:11] offset:2048 nt
	global_store_dwordx4 v104, v[52:55], s[10:11] offset:3072 nt
	global_store_dwordx4 v105, v[56:59], s[10:11] nt
	global_store_dwordx4 v105, v[60:63], s[10:11] offset:1024 nt
	global_store_dwordx4 v105, v[64:67], s[10:11] offset:2048 nt
	global_store_dwordx4 v105, v[68:71], s[10:11] offset:3072 nt
	global_store_dwordx4 v104, v[72:75], s[50:51] nt
	global_store_dwordx4 v104, v[76:79], s[50:51] offset:1024 nt
	global_store_dwordx4 v104, v[80:83], s[50:51] offset:2048 nt
	global_store_dwordx4 v104, v[84:87], s[50:51] offset:3072 nt
	global_store_dwordx4 v105, v[88:91], s[50:51] nt
	global_store_dwordx4 v105, v[92:95], s[50:51] offset:1024 nt
	global_store_dwordx4 v105, v[96:99], s[50:51] offset:2048 nt
	global_store_dwordx4 v105, v[100:103], s[50:51] offset:3072 nt
	s_add_i32 s5, s5, 2
	s_cmp_lt_u32 s5, 8
	s_cbranch_scc1 .Lcpw_trip_P7
	s_branch .Lcpw_loop_P7
.Lcpw_exit_P7:
	s_mov_b64 exec, s[62:63]
